# hand-off counter waits poll at s_sleep 12 instead of 8 (poll back-off: less poll traffic while producers run)
# speedup vs baseline: 1.0017x; 1.0017x over previous
.LBB0_1055:
	global_load_dword v3, v2, s[20:21] sc1
	s_mov_b64 s[22:23], -1
	s_waitcnt vmcnt(0)
	v_readfirstlane_b32 s5, v3
	s_cmp_ge_u32 s5, s33
	s_cbranch_scc1 .LBB0_1054
	s_sleep 12
	global_load_dword v3, v2, s[20:21] sc1
	s_waitcnt vmcnt(0)
	v_readfirstlane_b32 s5, v3
	s_cmp_lt_u32 s5, s33
	s_cbranch_scc0 .LBB0_1054
	s_sleep 12
	global_load_dword v3, v2, s[20:21] sc1
	s_waitcnt vmcnt(0)
	v_readfirstlane_b32 s5, v3
	s_cmp_lt_u32 s5, s33
	s_cbranch_scc0 .LBB0_1054
	s_sleep 12
	global_load_dword v3, v2, s[20:21] sc1
	s_waitcnt vmcnt(0)
	v_readfirstlane_b32 s5, v3
	s_cmp_lt_u32 s5, s33
	s_cbranch_scc0 .LBB0_1054
	s_sleep 12
	global_load_dword v3, v2, s[20:21] sc1
	s_waitcnt vmcnt(0)
	v_readfirstlane_b32 s5, v3
	s_cmp_lt_u32 s5, s33
	s_cbranch_scc0 .LBB0_1054
	s_add_i32 s4, s4, -5
	s_cmp_eq_u32 s4, 0
	s_cselect_b64 s[22:23], -1, 0
	s_sleep 12
	s_branch .LBB0_1054

.LBB0_1070:
	global_load_dword v3, v2, s[0:1] sc1
	s_mov_b64 s[18:19], -1
	s_waitcnt vmcnt(0)
	v_readfirstlane_b32 s5, v3
	s_cmp_ge_u32 s5, s94
	s_cbranch_scc1 .LBB0_1069
	s_sleep 12
	global_load_dword v3, v2, s[0:1] sc1
	s_waitcnt vmcnt(0)
	v_readfirstlane_b32 s5, v3
	s_cmp_lt_u32 s5, s94
	s_cbranch_scc0 .LBB0_1069
	s_sleep 12
	global_load_dword v3, v2, s[0:1] sc1
	s_waitcnt vmcnt(0)
	v_readfirstlane_b32 s5, v3
	s_cmp_lt_u32 s5, s94
	s_cbranch_scc0 .LBB0_1069
	s_sleep 12
	global_load_dword v3, v2, s[0:1] sc1
	s_waitcnt vmcnt(0)
	v_readfirstlane_b32 s5, v3
	s_cmp_lt_u32 s5, s94
	s_cbranch_scc0 .LBB0_1069
	s_sleep 12
	global_load_dword v3, v2, s[0:1] sc1
	s_waitcnt vmcnt(0)
	v_readfirstlane_b32 s5, v3
	s_cmp_lt_u32 s5, s94
	s_cbranch_scc0 .LBB0_1069
	s_add_i32 s4, s4, -5
	s_cmp_eq_u32 s4, 0
	s_cselect_b64 s[18:19], -1, 0
	s_sleep 12
	s_branch .LBB0_1069

.LBB0_1273:
	global_load_dword v3, v2, s[0:1] sc1
	s_mov_b64 s[18:19], -1
	s_waitcnt vmcnt(0)
	v_readfirstlane_b32 s5, v3
	s_cmp_ge_u32 s5, s36
	s_cbranch_scc1 .LBB0_1272
	s_sleep 12
	global_load_dword v3, v2, s[0:1] sc1
	s_waitcnt vmcnt(0)
	v_readfirstlane_b32 s5, v3
	s_cmp_lt_u32 s5, s36
	s_cbranch_scc0 .LBB0_1272
	s_sleep 12
	global_load_dword v3, v2, s[0:1] sc1
	s_waitcnt vmcnt(0)
	v_readfirstlane_b32 s5, v3
	s_cmp_lt_u32 s5, s36
	s_cbranch_scc0 .LBB0_1272
	s_sleep 12
	global_load_dword v3, v2, s[0:1] sc1
	s_waitcnt vmcnt(0)
	v_readfirstlane_b32 s5, v3
	s_cmp_lt_u32 s5, s36
	s_cbranch_scc0 .LBB0_1272
	s_sleep 12
	global_load_dword v3, v2, s[0:1] sc1
	s_waitcnt vmcnt(0)
	v_readfirstlane_b32 s5, v3
	s_cmp_lt_u32 s5, s36
	s_cbranch_scc0 .LBB0_1272
	s_add_i32 s4, s4, -5
	s_cmp_eq_u32 s4, 0
	s_cselect_b64 s[18:19], -1, 0
	s_sleep 12
	s_branch .LBB0_1272

.LBB0_1356:
	global_load_dword v3, v2, s[0:1] sc1
	s_mov_b64 s[18:19], -1
	s_waitcnt vmcnt(0)
	v_readfirstlane_b32 s9, v3
	s_cmp_ge_u32 s9, s94
	s_cbranch_scc1 .LBB0_1355
	s_sleep 12
	global_load_dword v3, v2, s[0:1] sc1
	s_waitcnt vmcnt(0)
	v_readfirstlane_b32 s9, v3
	s_cmp_lt_u32 s9, s94
	s_cbranch_scc0 .LBB0_1355
	s_sleep 12
	global_load_dword v3, v2, s[0:1] sc1
	s_waitcnt vmcnt(0)
	v_readfirstlane_b32 s9, v3
	s_cmp_lt_u32 s9, s94
	s_cbranch_scc0 .LBB0_1355
	s_sleep 12
	global_load_dword v3, v2, s[0:1] sc1
	s_waitcnt vmcnt(0)
	v_readfirstlane_b32 s9, v3
	s_cmp_lt_u32 s9, s94
	s_cbranch_scc0 .LBB0_1355
	s_sleep 12
	global_load_dword v3, v2, s[0:1] sc1
	s_waitcnt vmcnt(0)
	v_readfirstlane_b32 s9, v3
	s_cmp_lt_u32 s9, s94
	s_cbranch_scc0 .LBB0_1355
	s_add_i32 s6, s6, -5
	s_cmp_eq_u32 s6, 0
	s_cselect_b64 s[18:19], -1, 0
	s_sleep 12
	s_branch .LBB0_1355

.LBB0_1531:
	global_load_dword v2, v3, s[22:23] sc1
	s_waitcnt vmcnt(0)
	v_readfirstlane_b32 s0, v2
	s_cmp_ge_u32 s0, s94
	s_mov_b64 s[0:1], -1
	s_cbranch_scc1 .LBB0_1530
	s_sleep 12
	global_load_dword v2, v3, s[22:23] sc1
	s_waitcnt vmcnt(0)
	v_readfirstlane_b32 s0, v2
	s_cmp_lt_u32 s0, s94
	s_mov_b64 s[0:1], -1
	s_cbranch_scc0 .LBB0_1530
	s_sleep 12
	global_load_dword v2, v3, s[22:23] sc1
	s_waitcnt vmcnt(0)
	v_readfirstlane_b32 s0, v2
	s_cmp_lt_u32 s0, s94
	s_mov_b64 s[0:1], -1
	s_cbranch_scc0 .LBB0_1530
	s_sleep 12
	global_load_dword v2, v3, s[22:23] sc1
	s_waitcnt vmcnt(0)
	v_readfirstlane_b32 s0, v2
	s_cmp_lt_u32 s0, s94
	s_mov_b64 s[0:1], -1
	s_cbranch_scc0 .LBB0_1530
	s_sleep 12
	global_load_dword v2, v3, s[22:23] sc1
	s_waitcnt vmcnt(0)
	v_readfirstlane_b32 s0, v2
	s_cmp_lt_u32 s0, s94
	s_mov_b64 s[0:1], -1
	s_cbranch_scc0 .LBB0_1530
	s_add_i32 s4, s4, -5
	s_cmp_eq_u32 s4, 0
	s_cselect_b64 s[0:1], -1, 0
	s_sleep 12
	s_branch .LBB0_1530
